# v11 + scan pass 2: park the first three HM output stores of a chunk in the thread's own consumed T0 LDS block and issue all four global stores together after the 4th iteration
# speedup vs baseline: 1.0042x; 1.0042x over previous
.LBB0_773:
	s_or_b64 exec, exec, s[0:1]
	s_add_i32 s0, 0, 0x21000
	s_waitcnt lgkmcnt(0)
	s_barrier
	v_lshl_add_u32 v121, v143, 2, s0
	ds_read_b128 v[234:237], v121
	s_waitcnt lgkmcnt(1)
	v_lshlrev_b32_e32 v134, 6, v196
	v_cmp_gt_i32_e64 s[6:7], s86, v132
	v_or_b32_e32 v188, 1, v182
	s_and_b64 s[8:9], s[2:3], s[6:7]
	s_waitcnt lgkmcnt(0)
	v_mul_f32_e32 v48, v48, v234
	v_bfe_u32 v121, v48, 16, 1
	v_mul_f32_e32 v49, v49, v235
	v_add3_u32 v48, v48, v121, s68
	ds_write_b16_d16_hi v222, v48
	v_bfe_u32 v48, v49, 16, 1
	v_add3_u32 v48, v49, v48, s68
	ds_write_b16_d16_hi v225, v48
	v_mul_f32_e32 v48, v50, v236
	v_bfe_u32 v49, v48, 16, 1
	v_add3_u32 v48, v48, v49, s68
	ds_write_b16_d16_hi v229, v48
	v_lshl_add_u32 v48, v113, 2, s0
	ds_read_b128 v[238:241], v48
	v_mul_f32_e32 v48, v51, v237
	v_bfe_u32 v49, v48, 16, 1
	v_add3_u32 v48, v48, v49, s68
	ds_write_b16_d16_hi v211, v48
	s_waitcnt lgkmcnt(1)
	v_mul_f32_e32 v48, v52, v238
	v_bfe_u32 v49, v48, 16, 1
	v_add3_u32 v48, v48, v49, s68
	ds_write_b16_d16_hi v207, v48
	v_mul_f32_e32 v48, v53, v239
	v_bfe_u32 v49, v48, 16, 1
	v_add3_u32 v48, v48, v49, s68
	ds_write_b16_d16_hi v210, v48
	v_mul_f32_e32 v48, v54, v240
	v_bfe_u32 v49, v48, 16, 1
	v_add3_u32 v48, v48, v49, s68
	ds_write_b16_d16_hi v214, v48
	v_lshl_add_u32 v48, v126, 2, s0
	ds_read_b128 v[48:51], v48
	v_mul_f32_e32 v52, v55, v241
	v_bfe_u32 v53, v52, 16, 1
	v_add3_u32 v52, v52, v53, s68
	ds_write_b16_d16_hi v213, v52
	s_waitcnt lgkmcnt(1)
	v_mul_f32_e32 v52, v56, v48
	v_bfe_u32 v53, v52, 16, 1
	v_add3_u32 v52, v52, v53, s68
	ds_write_b16_d16_hi v215, v52
	v_mul_f32_e32 v52, v57, v49
	v_bfe_u32 v53, v52, 16, 1
	v_add3_u32 v52, v52, v53, s68
	ds_write_b16_d16_hi v217, v52
	v_mul_f32_e32 v52, v58, v50
	v_bfe_u32 v53, v52, 16, 1
	v_add3_u32 v52, v52, v53, s68
	ds_write_b16_d16_hi v219, v52
	v_lshl_add_u32 v52, v123, 2, s0
	ds_read_b128 v[52:55], v52
	v_mul_f32_e32 v56, v59, v51
	v_bfe_u32 v57, v56, 16, 1
	v_add3_u32 v56, v56, v57, s68
	ds_write_b16_d16_hi v204, v56
	s_waitcnt lgkmcnt(1)
	v_mul_f32_e32 v56, v60, v52
	v_bfe_u32 v57, v56, 16, 1
	v_add3_u32 v56, v56, v57, s68
	ds_write_b16_d16_hi v202, v56
	v_mul_f32_e32 v56, v61, v53
	v_bfe_u32 v57, v56, 16, 1
	v_add3_u32 v56, v56, v57, s68
	ds_write_b16_d16_hi v203, v56
	v_mul_f32_e32 v56, v62, v54
	v_bfe_u32 v57, v56, 16, 1
	v_add3_u32 v56, v56, v57, s68
	ds_write_b16_d16_hi v205, v56
	v_mul_f32_e32 v56, v63, v55
	v_bfe_u32 v57, v56, 16, 1
	v_add3_u32 v56, v56, v57, s68
	v_mul_f32_e32 v32, v32, v234
	ds_write_b16_d16_hi v206, v56
	v_bfe_u32 v56, v32, 16, 1
	v_add3_u32 v32, v32, v56, s68
	ds_write_b16_d16_hi v208, v32
	v_mul_f32_e32 v32, v33, v235
	v_bfe_u32 v33, v32, 16, 1
	v_add3_u32 v32, v32, v33, s68
	ds_write_b16_d16_hi v209, v32
	v_mul_f32_e32 v32, v34, v236
	v_bfe_u32 v33, v32, 16, 1
	v_add3_u32 v32, v32, v33, s68
	ds_write_b16_d16_hi v212, v32
	v_mul_f32_e32 v32, v35, v237
	v_bfe_u32 v33, v32, 16, 1
	v_add3_u32 v32, v32, v33, s68
	ds_write_b16_d16_hi v216, v32
	v_mul_f32_e32 v32, v36, v238
	v_bfe_u32 v33, v32, 16, 1
	v_add3_u32 v32, v32, v33, s68
	ds_write_b16_d16_hi v218, v32
	v_mul_f32_e32 v32, v37, v239
	v_bfe_u32 v33, v32, 16, 1
	v_add3_u32 v32, v32, v33, s68
	ds_write_b16_d16_hi v220, v32
	v_mul_f32_e32 v32, v38, v240
	v_bfe_u32 v33, v32, 16, 1
	v_add3_u32 v32, v32, v33, s68
	ds_write_b16_d16_hi v221, v32
	v_mul_f32_e32 v32, v39, v241
	v_bfe_u32 v33, v32, 16, 1
	v_add3_u32 v32, v32, v33, s68
	ds_write_b16_d16_hi v223, v32
	v_mul_f32_e32 v32, v40, v48
	v_bfe_u32 v33, v32, 16, 1
	v_add3_u32 v32, v32, v33, s68
	ds_write_b16_d16_hi v224, v32
	v_mul_f32_e32 v32, v41, v49
	v_bfe_u32 v33, v32, 16, 1
	v_add3_u32 v32, v32, v33, s68
	ds_write_b16_d16_hi v226, v32
	v_mul_f32_e32 v32, v42, v50
	v_bfe_u32 v33, v32, 16, 1
	v_add3_u32 v32, v32, v33, s68
	ds_write_b16_d16_hi v227, v32
	v_mul_f32_e32 v32, v43, v51
	v_bfe_u32 v33, v32, 16, 1
	v_add3_u32 v32, v32, v33, s68
	ds_write_b16_d16_hi v228, v32
	v_mul_f32_e32 v32, v44, v52
	v_bfe_u32 v33, v32, 16, 1
	v_add3_u32 v32, v32, v33, s68
	ds_write_b16_d16_hi v230, v32
	v_mul_f32_e32 v32, v45, v53
	v_bfe_u32 v33, v32, 16, 1
	v_add3_u32 v32, v32, v33, s68
	ds_write_b16_d16_hi v231, v32
	v_mul_f32_e32 v32, v46, v54
	v_bfe_u32 v33, v32, 16, 1
	v_add3_u32 v32, v32, v33, s68
	ds_write_b16_d16_hi v232, v32
	v_mul_f32_e32 v32, v47, v55
	v_bfe_u32 v33, v32, 16, 1
	v_add3_u32 v32, v32, v33, s68
	v_ashrrev_i32_e32 v121, 31, v120
	ds_write_b16_d16_hi v233, v32
	v_lshl_add_u64 v[32:33], s[66:67], 0, v[120:121]
	v_lshlrev_b64 v[34:35], 13, v[32:33]
	v_lshl_add_u64 v[38:39], s[52:53], 0, v[34:35]
	s_waitcnt lgkmcnt(0)
	s_barrier
	v_lshl_add_u64 v[34:35], v[38:39], 0, v[134:135]
	global_load_dwordx4 v[40:43], v[34:35], off offset:3072
	v_lshlrev_b32_e32 v121, 7, v196
	global_load_dwordx4 v[48:51], v121, s[18:19]
	ds_read_b128 v[44:47], v117
	ds_read_b128 v[52:55], v191
	ds_read_b128 v[56:59], v190
	ds_read_b128 v[60:63], v161
	global_load_dwordx4 v[200:203], v121, s[18:19] offset:16
	s_waitcnt lgkmcnt(3)
	v_and_b32_e32 v34, 0xffff0000, v46
	v_lshlrev_b32_e32 v35, 16, v46
	v_and_b32_e32 v36, 0xffff0000, v47
	v_lshlrev_b32_e32 v37, 16, v47
	s_waitcnt lgkmcnt(2)
	v_lshlrev_b32_e32 v209, 16, v53
	v_lshlrev_b32_e32 v208, 16, v52
	v_and_b32_e32 v53, 0xffff0000, v53
	v_and_b32_e32 v52, 0xffff0000, v52
	v_pk_mul_f32 v[210:211], v[208:209], v[208:209]
	v_pk_mul_f32 v[212:213], v[52:53], v[52:53]
	v_lshlrev_b32_e32 v221, 16, v55
	v_lshlrev_b32_e32 v220, 16, v54
	v_and_b32_e32 v55, 0xffff0000, v55
	v_and_b32_e32 v54, 0xffff0000, v54
	v_pk_mul_f32 v[222:223], v[220:221], v[220:221]
	v_pk_mul_f32 v[224:225], v[54:55], v[54:55]
	s_waitcnt lgkmcnt(1)
	v_lshlrev_b32_e32 v235, 16, v57
	v_lshlrev_b32_e32 v234, 16, v56
	v_and_b32_e32 v237, 0xffff0000, v57
	v_and_b32_e32 v236, 0xffff0000, v56
	v_pk_mul_f32 v[56:57], v[234:235], v[234:235]
	v_pk_mul_f32 v[238:239], v[236:237], v[236:237]
	v_lshlrev_b32_e32 v241, 16, v59
	v_lshlrev_b32_e32 v240, 16, v58
	v_and_b32_e32 v243, 0xffff0000, v59
	v_and_b32_e32 v242, 0xffff0000, v58
	v_pk_mul_f32 v[58:59], v[240:241], v[240:241]
	v_pk_mul_f32 v[244:245], v[242:243], v[242:243]
	s_waitcnt lgkmcnt(0)
	v_lshlrev_b32_e32 v247, 16, v61
	v_lshlrev_b32_e32 v246, 16, v60
	v_and_b32_e32 v249, 0xffff0000, v61
	v_and_b32_e32 v248, 0xffff0000, v60
	v_pk_mul_f32 v[60:61], v[246:247], v[246:247]
	v_pk_mul_f32 v[250:251], v[248:249], v[248:249]
	v_pk_mul_f32 v[204:205], v[34:35], v[34:35]
	v_pk_mul_f32 v[206:207], v[36:37], v[36:37]
	v_lshlrev_b64 v[32:33], 11, v[32:33]
	v_lshl_add_u64 v[32:33], s[54:55], 0, v[32:33]
	s_waitcnt vmcnt(2)
	v_lshlrev_b32_e32 v46, 16, v40
	v_mul_f32_e32 v47, 0xbfb8aa3b, v46
	v_exp_f32_e32 v136, v47
	v_lshlrev_b32_e32 v47, 16, v41
	v_and_b32_e32 v41, 0xffff0000, v41
	v_and_b32_e32 v40, 0xffff0000, v40
	v_mul_f32_e32 v137, 0xbfb8aa3b, v40
	v_mul_f32_e32 v121, 0xbfb8aa3b, v41
	v_exp_f32_e32 v137, v137
	v_exp_f32_e32 v121, v121
	v_mul_f32_e32 v189, 0xbfb8aa3b, v47
	v_exp_f32_e32 v189, v189
	v_add_f32_e32 v136, 1.0, v136
	v_rcp_f32_e32 v214, v136
	v_add_f32_e32 v136, 1.0, v137
	s_waitcnt vmcnt(1)
	v_mov_b32_e32 v218, v48
	v_add_f32_e32 v48, 1.0, v121
	v_rcp_f32_e32 v216, v136
	v_rcp_f32_e32 v217, v48
	v_add_f32_e32 v121, v210, v212
	v_add_f32_e32 v136, 1.0, v189
	v_add_f32_e32 v121, v211, v121
	v_rcp_f32_e32 v215, v136
	v_add_f32_e32 v121, v213, v121
	v_add_f32_e32 v121, v222, v121
	v_pk_mul_f32 v[40:41], v[216:217], v[40:41]
	v_add_f32_e32 v121, v224, v121
	v_cndmask_b32_e64 v216, v40, v216, s[2:3]
	v_lshlrev_b32_e32 v40, 16, v42
	v_add_f32_e32 v121, v223, v121
	v_pk_mul_f32 v[46:47], v[214:215], v[46:47]
	v_cndmask_b32_e64 v217, v41, v217, s[2:3]
	v_mul_f32_e32 v41, 0xbfb8aa3b, v40
	v_add_f32_e32 v121, v225, v121
	v_cndmask_b32_e64 v214, v46, v214, s[2:3]
	v_exp_f32_e32 v46, v41
	v_lshlrev_b32_e32 v41, 16, v43
	v_add_f32_e32 v56, v56, v121
	v_and_b32_e32 v227, 0xffff0000, v43
	v_mul_f32_e32 v43, 0xbfb8aa3b, v41
	v_add_f32_e32 v56, v238, v56
	v_exp_f32_e32 v43, v43
	v_add_f32_e32 v56, v57, v56
	v_add_f32_e32 v56, v239, v56
	v_add_f32_e32 v56, v58, v56
	v_add_f32_e32 v56, v244, v56
	v_add_f32_e32 v43, 1.0, v43
	v_add_f32_e32 v56, v59, v56
	v_and_b32_e32 v226, 0xffff0000, v42
	v_add_f32_e32 v42, 1.0, v46
	v_rcp_f32_e32 v229, v43
	v_mul_f32_e32 v43, 0xbfb8aa3b, v227
	v_add_f32_e32 v56, v245, v56
	v_rcp_f32_e32 v228, v42
	v_exp_f32_e32 v43, v43
	v_add_f32_e32 v56, v60, v56
	v_add_f32_e32 v56, v250, v56
	v_mov_b32_e32 v219, v50
	v_mov_b32_e32 v50, v49
	v_mul_f32_e32 v42, 0xbfb8aa3b, v226
	v_lshlrev_b32_e32 v49, 16, v63
	v_lshlrev_b32_e32 v48, 16, v62
	v_add_f32_e32 v56, v61, v56
	v_cndmask_b32_e64 v215, v47, v215, s[2:3]
	v_exp_f32_e32 v42, v42
	v_and_b32_e32 v47, 0xffff0000, v63
	v_and_b32_e32 v46, 0xffff0000, v62
	v_pk_mul_f32 v[62:63], v[48:49], v[48:49]
	v_add_f32_e32 v56, v251, v56
	v_pk_mul_f32 v[232:233], v[228:229], v[40:41]
	v_add_f32_e32 v40, 1.0, v43
	v_pk_mul_f32 v[252:253], v[46:47], v[46:47]
	v_add_f32_e32 v56, v62, v56
	v_rcp_f32_e32 v231, v40
	v_lshlrev_b32_e32 v136, 16, v44
	v_and_b32_e32 v40, 0xffff0000, v44
	v_add_f32_e32 v56, v252, v56
	v_lshlrev_b32_e32 v137, 16, v45
	v_and_b32_e32 v41, 0xffff0000, v45
	v_mov_b32_e32 v44, v40
	v_mov_b32_e32 v45, v136
	v_add_f32_e32 v56, v63, v56
	v_add_f32_e32 v42, 1.0, v42
	v_pk_mul_f32 v[44:45], v[44:45], v[44:45]
	v_add_f32_e32 v56, v253, v56
	v_rcp_f32_e32 v230, v42
	v_mov_b32_e32 v42, v41
	v_mov_b32_e32 v43, v137
	v_add_f32_e32 v45, v45, v56
	v_pk_mul_f32 v[42:43], v[42:43], v[42:43]
	v_add_f32_e32 v44, v44, v45
	v_add_f32_e32 v43, v43, v44
	v_add_f32_e32 v42, v42, v43
	v_add_f32_e32 v42, v205, v42
	v_add_f32_e32 v42, v204, v42
	v_add_f32_e32 v42, v207, v42
	v_add_f32_e32 v56, v206, v42
	ds_bpermute_b32 v58, v197, v56
	v_pk_mul_f32 v[44:45], v[230:231], v[226:227]
	s_waitcnt vmcnt(0)
	v_mov_b32_e32 v59, v202
	v_cndmask_b32_e64 v57, v45, v231, s[2:3]
	v_cndmask_b32_e64 v43, v233, v229, s[2:3]
	s_waitcnt lgkmcnt(0)
	v_add_f32_e32 v45, v56, v58
	ds_bpermute_b32 v60, v198, v45
	v_cndmask_b32_e64 v56, v44, v230, s[2:3]
	v_mov_b32_e32 v58, v200
	v_cndmask_b32_e64 v42, v232, v228, s[2:3]
	v_mov_b32_e32 v202, v201
	s_waitcnt lgkmcnt(0)
	v_add_f32_e32 v44, v45, v60
	v_fmamk_f32 v44, v44, 0x3c000000, v133
	v_cmp_gt_f32_e32 vcc, s85, v44
	v_mul_f32_e32 v45, 0x4b800000, v44
	v_lshl_add_u64 v[60:61], v[32:33], 0, v[134:135]
	v_cndmask_b32_e32 v44, v44, v45, vcc
	v_rsq_f32_e32 v44, v44
	v_lshlrev_b32_e32 v134, 4, v195
	v_lshl_add_u64 v[62:63], v[38:39], 0, v[134:135]
	v_mul_f32_e32 v45, 0x45800000, v44
	v_cndmask_b32_e32 v44, v44, v45, vcc
	v_pk_mul_f32 v[52:53], v[44:45], v[52:53] op_sel_hi:[0,1]
	v_pk_mul_f32 v[50:51], v[50:51], v[52:53]
	v_pk_mul_f32 v[52:53], v[44:45], v[220:221] op_sel_hi:[0,1]
	v_pk_mul_f32 v[52:53], v[58:59], v[52:53]
	v_pk_mul_f32 v[196:197], v[44:45], v[208:209] op_sel_hi:[0,1]
	v_pk_mul_f32 v[42:43], v[42:43], v[52:53]
	v_pk_mul_f32 v[52:53], v[44:45], v[54:55] op_sel_hi:[0,1]
	v_pk_mul_f32 v[52:53], v[202:203], v[52:53]
	v_pk_mul_f32 v[196:197], v[218:219], v[196:197]
	v_pk_mul_f32 v[50:51], v[216:217], v[50:51]
	v_pk_mul_f32 v[52:53], v[56:57], v[52:53]
	v_pk_mul_f32 v[196:197], v[214:215], v[196:197]
	v_bfe_u32 v45, v53, 16, 1
	v_bfe_u32 v54, v52, 16, 1
	v_bfe_u32 v55, v51, 16, 1
	v_bfe_u32 v56, v50, 16, 1
	v_add3_u32 v50, v50, v56, s68
	v_add3_u32 v51, v51, v55, s68
	v_add3_u32 v52, v52, v54, s68
	v_add3_u32 v45, v53, v45, s68
	v_bfe_u32 v53, v196, 16, 1
	v_bfe_u32 v54, v197, 16, 1
	v_bfe_u32 v55, v42, 16, 1
	v_bfe_u32 v56, v43, 16, 1
	v_add3_u32 v43, v43, v56, s68
	v_add3_u32 v42, v42, v55, s68
	v_add3_u32 v54, v197, v54, s68
	v_add3_u32 v53, v196, v53, s68
	v_lshrrev_b32_e32 v55, 16, v53
	v_lshrrev_b32_e32 v54, 16, v54
	v_lshrrev_b32_e32 v42, 16, v42
	v_lshrrev_b32_e32 v43, 16, v43
	v_and_or_b32 v53, v45, s82, v43
	v_and_or_b32 v52, v52, s82, v42
	v_and_or_b32 v51, v51, s82, v54
	v_and_or_b32 v50, v50, s82, v55
	v_and_b32_e32 v60, 0xffffffc0, v191
	ds_write_b128 v60, v[50:53]
	global_load_dwordx4 v[50:53], v[62:63], off offset:3072
	v_lshlrev_b32_e32 v42, 5, v195
	global_load_dwordx4 v[54:57], v42, s[18:19]
	global_load_dwordx4 v[58:61], v42, s[18:19] offset:16
	v_lshl_add_u64 v[42:43], v[32:33], 0, v[134:135]
	v_lshlrev_b32_e32 v134, 4, v194
	v_lshl_add_u64 v[62:63], v[38:39], 0, v[134:135]
	s_waitcnt vmcnt(2)
	v_lshlrev_b32_e32 v196, 16, v50
	v_and_b32_e32 v50, 0xffff0000, v50
	v_mul_f32_e32 v45, 0xbfb8aa3b, v196
	v_lshlrev_b32_e32 v197, 16, v51
	v_exp_f32_e32 v45, v45
	v_mul_f32_e32 v121, 0xbfb8aa3b, v50
	v_exp_f32_e32 v121, v121
	v_mul_f32_e32 v189, 0xbfb8aa3b, v197
	v_exp_f32_e32 v189, v189
	v_add_f32_e32 v45, 1.0, v45
	v_rcp_f32_e32 v200, v45
	v_add_f32_e32 v45, 1.0, v121
	v_and_b32_e32 v51, 0xffff0000, v51
	v_rcp_f32_e32 v202, v45
	v_add_f32_e32 v45, 1.0, v189
	v_rcp_f32_e32 v201, v45
	v_pk_mul_f32 v[204:205], v[44:45], v[234:235] op_sel_hi:[0,1]
	v_mul_f32_e32 v45, 0xbfb8aa3b, v51
	v_exp_f32_e32 v45, v45
	v_pk_mul_f32 v[196:197], v[200:201], v[196:197]
	v_lshlrev_b32_e32 v198, 16, v52
	s_waitcnt vmcnt(1)
	v_mov_b32_e32 v207, v56
	v_add_f32_e32 v45, 1.0, v45
	v_rcp_f32_e32 v203, v45
	v_cndmask_b32_e64 v197, v197, v201, s[2:3]
	v_cndmask_b32_e64 v196, v196, v200, s[2:3]
	v_pk_mul_f32 v[200:201], v[44:45], v[236:237] op_sel_hi:[0,1]
	v_mov_b32_e32 v56, v55
	v_pk_mul_f32 v[50:51], v[202:203], v[50:51]
	v_and_b32_e32 v52, 0xffff0000, v52
	v_mov_b32_e32 v206, v54
	v_pk_mul_f32 v[54:55], v[56:57], v[200:201]
	v_mul_f32_e32 v45, 0xbfb8aa3b, v198
	v_cndmask_b32_e64 v51, v51, v203, s[2:3]
	v_cndmask_b32_e64 v50, v50, v202, s[2:3]
	v_lshlrev_b32_e32 v199, 16, v53
	v_exp_f32_e32 v45, v45
	v_pk_mul_f32 v[50:51], v[50:51], v[54:55]
	v_mul_f32_e32 v54, 0xbfb8aa3b, v52
	v_exp_f32_e32 v55, v54
	v_mul_f32_e32 v54, 0xbfb8aa3b, v199
	v_exp_f32_e32 v57, v54
	v_add_f32_e32 v45, 1.0, v45
	v_rcp_f32_e32 v54, v45
	v_add_f32_e32 v45, 1.0, v55
	v_and_b32_e32 v53, 0xffff0000, v53
	v_rcp_f32_e32 v56, v45
	v_add_f32_e32 v45, 1.0, v57
	v_rcp_f32_e32 v55, v45
	v_pk_mul_f32 v[200:201], v[44:45], v[240:241] op_sel_hi:[0,1]
	v_mul_f32_e32 v45, 0xbfb8aa3b, v53
	v_exp_f32_e32 v45, v45
	v_pk_mul_f32 v[198:199], v[54:55], v[198:199]
	s_waitcnt vmcnt(0)
	v_mov_b32_e32 v203, v60
	v_cndmask_b32_e64 v55, v199, v55, s[2:3]
	v_add_f32_e32 v45, 1.0, v45
	v_rcp_f32_e32 v57, v45
	v_cndmask_b32_e64 v54, v198, v54, s[2:3]
	v_pk_mul_f32 v[198:199], v[44:45], v[242:243] op_sel_hi:[0,1]
	v_mov_b32_e32 v60, v59
	v_pk_mul_f32 v[52:53], v[56:57], v[52:53]
	v_mov_b32_e32 v202, v58
	v_pk_mul_f32 v[58:59], v[60:61], v[198:199]
	v_cndmask_b32_e64 v53, v53, v57, s[2:3]
	v_cndmask_b32_e64 v52, v52, v56, s[2:3]
	v_pk_mul_f32 v[204:205], v[206:207], v[204:205]
	v_pk_mul_f32 v[200:201], v[202:203], v[200:201]
	v_pk_mul_f32 v[52:53], v[52:53], v[58:59]
	v_pk_mul_f32 v[196:197], v[196:197], v[204:205]
	v_pk_mul_f32 v[54:55], v[54:55], v[200:201]
	v_bfe_u32 v45, v53, 16, 1
	v_bfe_u32 v56, v52, 16, 1
	v_bfe_u32 v57, v51, 16, 1
	v_bfe_u32 v58, v50, 16, 1
	v_add3_u32 v50, v50, v58, s68
	v_add3_u32 v51, v51, v57, s68
	v_add3_u32 v52, v52, v56, s68
	v_add3_u32 v45, v53, v45, s68
	v_bfe_u32 v53, v196, 16, 1
	v_bfe_u32 v56, v197, 16, 1
	v_bfe_u32 v57, v54, 16, 1
	v_bfe_u32 v58, v55, 16, 1
	v_add3_u32 v55, v55, v58, s68
	v_add3_u32 v54, v54, v57, s68
	v_add3_u32 v56, v197, v56, s68
	v_add3_u32 v53, v196, v53, s68
	v_lshrrev_b32_e32 v57, 16, v53
	v_lshrrev_b32_e32 v56, 16, v56
	v_lshrrev_b32_e32 v54, 16, v54
	v_lshrrev_b32_e32 v53, 16, v55
	v_and_or_b32 v53, v45, s82, v53
	v_and_or_b32 v52, v52, s82, v54
	v_and_or_b32 v51, v51, s82, v56
	v_and_or_b32 v50, v50, s82, v57
	v_and_b32_e32 v42, 0xffffffc0, v191
	ds_write_b128 v42, v[50:53] offset:16
	global_load_dwordx4 v[50:53], v[62:63], off offset:3072
	v_lshlrev_b32_e32 v42, 5, v194
	global_load_dwordx4 v[54:57], v42, s[18:19]
	global_load_dwordx4 v[58:61], v42, s[18:19] offset:16
	v_lshl_add_u64 v[42:43], v[32:33], 0, v[134:135]
	v_lshlrev_b32_e32 v134, 4, v193
	v_lshl_add_u64 v[38:39], v[38:39], 0, v[134:135]
	v_lshl_add_u64 v[32:33], v[32:33], 0, v[134:135]
	s_waitcnt vmcnt(2)
	v_lshlrev_b32_e32 v62, 16, v50
	v_and_b32_e32 v50, 0xffff0000, v50
	v_mul_f32_e32 v45, 0xbfb8aa3b, v62
	v_lshlrev_b32_e32 v63, 16, v51
	v_exp_f32_e32 v45, v45
	v_mul_f32_e32 v121, 0xbfb8aa3b, v50
	v_exp_f32_e32 v121, v121
	v_mul_f32_e32 v189, 0xbfb8aa3b, v63
	v_exp_f32_e32 v189, v189
	v_add_f32_e32 v45, 1.0, v45
	v_rcp_f32_e32 v196, v45
	v_add_f32_e32 v45, 1.0, v121
	v_and_b32_e32 v51, 0xffff0000, v51
	v_rcp_f32_e32 v198, v45
	v_add_f32_e32 v45, 1.0, v189
	v_rcp_f32_e32 v197, v45
	v_pk_mul_f32 v[200:201], v[44:45], v[246:247] op_sel_hi:[0,1]
	v_mul_f32_e32 v45, 0xbfb8aa3b, v51
	v_exp_f32_e32 v45, v45
	v_pk_mul_f32 v[62:63], v[196:197], v[62:63]
	v_lshlrev_b32_e32 v194, 16, v52
	s_waitcnt vmcnt(1)
	v_mov_b32_e32 v203, v56
	v_add_f32_e32 v45, 1.0, v45
	v_rcp_f32_e32 v199, v45
	v_cndmask_b32_e64 v63, v63, v197, s[2:3]
	v_cndmask_b32_e64 v62, v62, v196, s[2:3]
	v_pk_mul_f32 v[196:197], v[44:45], v[248:249] op_sel_hi:[0,1]
	v_mov_b32_e32 v56, v55
	v_pk_mul_f32 v[50:51], v[198:199], v[50:51]
	v_and_b32_e32 v52, 0xffff0000, v52
	v_mov_b32_e32 v202, v54
	v_pk_mul_f32 v[54:55], v[56:57], v[196:197]
	v_mul_f32_e32 v45, 0xbfb8aa3b, v194
	v_cndmask_b32_e64 v51, v51, v199, s[2:3]
	v_cndmask_b32_e64 v50, v50, v198, s[2:3]
	v_lshlrev_b32_e32 v195, 16, v53
	v_exp_f32_e32 v45, v45
	v_pk_mul_f32 v[50:51], v[50:51], v[54:55]
	v_mul_f32_e32 v54, 0xbfb8aa3b, v52
	v_exp_f32_e32 v55, v54
	v_mul_f32_e32 v54, 0xbfb8aa3b, v195
	v_exp_f32_e32 v57, v54
	v_add_f32_e32 v45, 1.0, v45
	v_rcp_f32_e32 v54, v45
	v_add_f32_e32 v45, 1.0, v55
	v_and_b32_e32 v53, 0xffff0000, v53
	v_rcp_f32_e32 v56, v45
	v_add_f32_e32 v45, 1.0, v57
	v_rcp_f32_e32 v55, v45
	v_pk_mul_f32 v[48:49], v[44:45], v[48:49] op_sel_hi:[0,1]
	v_mul_f32_e32 v45, 0xbfb8aa3b, v53
	v_exp_f32_e32 v45, v45
	s_waitcnt vmcnt(0)
	v_mov_b32_e32 v197, v60
	v_mov_b32_e32 v60, v59
	v_mov_b32_e32 v196, v58
	v_add_f32_e32 v45, 1.0, v45
	v_rcp_f32_e32 v57, v45
	v_pk_mul_f32 v[46:47], v[44:45], v[46:47] op_sel_hi:[0,1]
	v_pk_mul_f32 v[194:195], v[54:55], v[194:195]
	v_pk_mul_f32 v[46:47], v[60:61], v[46:47]
	v_pk_mul_f32 v[52:53], v[56:57], v[52:53]
	v_pk_mul_f32 v[200:201], v[202:203], v[200:201]
	v_cndmask_b32_e64 v53, v53, v57, s[2:3]
	v_cndmask_b32_e64 v52, v52, v56, s[2:3]
	v_pk_mul_f32 v[48:49], v[196:197], v[48:49]
	v_cndmask_b32_e64 v55, v195, v55, s[2:3]
	v_cndmask_b32_e64 v54, v194, v54, s[2:3]
	v_pk_mul_f32 v[46:47], v[52:53], v[46:47]
	v_pk_mul_f32 v[62:63], v[62:63], v[200:201]
	v_pk_mul_f32 v[48:49], v[54:55], v[48:49]
	v_bfe_u32 v45, v47, 16, 1
	v_bfe_u32 v52, v46, 16, 1
	v_bfe_u32 v53, v51, 16, 1
	v_bfe_u32 v54, v50, 16, 1
	v_add3_u32 v50, v50, v54, s68
	v_add3_u32 v51, v51, v53, s68
	v_add3_u32 v46, v46, v52, s68
	v_add3_u32 v45, v47, v45, s68
	v_bfe_u32 v47, v62, 16, 1
	v_bfe_u32 v52, v63, 16, 1
	v_bfe_u32 v53, v48, 16, 1
	v_bfe_u32 v54, v49, 16, 1
	v_add3_u32 v49, v49, v54, s68
	v_add3_u32 v48, v48, v53, s68
	v_add3_u32 v52, v63, v52, s68
	v_add3_u32 v47, v62, v47, s68
	v_lshrrev_b32_e32 v53, 16, v47
	v_lshrrev_b32_e32 v47, 16, v52
	v_lshrrev_b32_e32 v48, 16, v48
	v_lshrrev_b32_e32 v49, 16, v49
	v_and_or_b32 v49, v45, s82, v49
	v_and_or_b32 v48, v46, s82, v48
	v_and_or_b32 v47, v51, s82, v47
	v_and_or_b32 v46, v50, s82, v53
	v_and_b32_e32 v42, 0xffffffc0, v191
	ds_write_b128 v42, v[46:49] offset:32
	global_load_dwordx4 v[46:49], v[38:39], off offset:3072
	v_lshlrev_b32_e32 v38, 5, v193
	global_load_dwordx4 v[50:53], v38, s[18:19]
	global_load_dwordx4 v[54:57], v38, s[18:19] offset:16
	s_waitcnt vmcnt(2)
	v_lshlrev_b32_e32 v38, 16, v46
	v_mul_f32_e32 v39, 0xbfb8aa3b, v38
	v_and_b32_e32 v42, 0xffff0000, v46
	v_exp_f32_e32 v45, v39
	v_lshlrev_b32_e32 v39, 16, v47
	v_mul_f32_e32 v46, 0xbfb8aa3b, v42
	v_and_b32_e32 v43, 0xffff0000, v47
	v_exp_f32_e32 v47, v46
	v_mul_f32_e32 v46, 0xbfb8aa3b, v39
	v_exp_f32_e32 v59, v46
	v_add_f32_e32 v45, 1.0, v45
	v_rcp_f32_e32 v46, v45
	v_add_f32_e32 v45, 1.0, v47
	v_rcp_f32_e32 v58, v45
	v_add_f32_e32 v45, 1.0, v59
	v_rcp_f32_e32 v47, v45
	v_pk_mul_f32 v[60:61], v[44:45], v[136:137] op_sel_hi:[0,1]
	v_mul_f32_e32 v45, 0xbfb8aa3b, v43
	v_exp_f32_e32 v45, v45
	s_waitcnt vmcnt(1)
	v_mov_b32_e32 v63, v52
	v_mov_b32_e32 v52, v51
	v_pk_mul_f32 v[38:39], v[46:47], v[38:39]
	v_add_f32_e32 v45, 1.0, v45
	v_rcp_f32_e32 v59, v45
	v_pk_mul_f32 v[40:41], v[44:45], v[40:41] op_sel_hi:[0,1]
	v_pk_mul_f32 v[40:41], v[52:53], v[40:41]
	v_cndmask_b32_e64 v39, v39, v47, s[2:3]
	v_pk_mul_f32 v[42:43], v[58:59], v[42:43]
	v_cndmask_b32_e64 v38, v38, v46, s[2:3]
	v_cndmask_b32_e64 v43, v43, v59, s[2:3]
	v_cndmask_b32_e64 v42, v42, v58, s[2:3]
	v_pk_mul_f32 v[40:41], v[42:43], v[40:41]
	v_lshlrev_b32_e32 v42, 16, v48
	v_mul_f32_e32 v43, 0xbfb8aa3b, v42
	v_and_b32_e32 v47, 0xffff0000, v49
	v_and_b32_e32 v46, 0xffff0000, v48
	v_exp_f32_e32 v45, v43
	v_lshlrev_b32_e32 v43, 16, v49
	v_mul_f32_e32 v48, 0xbfb8aa3b, v46
	v_mov_b32_e32 v52, v35
	v_mul_f32_e32 v35, 0xbfb8aa3b, v47
	v_exp_f32_e32 v49, v48
	v_mul_f32_e32 v48, 0xbfb8aa3b, v43
	v_exp_f32_e32 v35, v35
	v_exp_f32_e32 v51, v48
	v_add_f32_e32 v45, 1.0, v45
	v_rcp_f32_e32 v48, v45
	v_add_f32_e32 v45, 1.0, v49
	v_add_f32_e32 v35, 1.0, v35
	v_mov_b32_e32 v62, v50
	v_rcp_f32_e32 v50, v45
	v_add_f32_e32 v45, 1.0, v51
	v_rcp_f32_e32 v51, v35
	v_rcp_f32_e32 v49, v45
	v_mov_b32_e32 v35, v36
	v_mov_b32_e32 v53, v37
	s_waitcnt vmcnt(0)
	v_mov_b32_e32 v59, v56
	v_pk_mul_f32 v[34:35], v[44:45], v[34:35] op_sel_hi:[0,1]
	v_mov_b32_e32 v56, v55
	v_pk_mul_f32 v[36:37], v[50:51], v[46:47]
	v_pk_mul_f32 v[52:53], v[44:45], v[52:53] op_sel_hi:[0,1]
	v_mov_b32_e32 v58, v54
	v_pk_mul_f32 v[42:43], v[48:49], v[42:43]
	v_pk_mul_f32 v[34:35], v[56:57], v[34:35]
	v_cndmask_b32_e64 v37, v37, v51, s[2:3]
	v_cndmask_b32_e64 v36, v36, v50, s[2:3]
	v_pk_mul_f32 v[60:61], v[62:63], v[60:61]
	v_pk_mul_f32 v[52:53], v[58:59], v[52:53]
	v_cndmask_b32_e64 v43, v43, v49, s[2:3]
	v_cndmask_b32_e64 v42, v42, v48, s[2:3]
	v_pk_mul_f32 v[34:35], v[36:37], v[34:35]
	v_pk_mul_f32 v[38:39], v[38:39], v[60:61]
	v_pk_mul_f32 v[42:43], v[42:43], v[52:53]
	v_bfe_u32 v36, v35, 16, 1
	v_bfe_u32 v37, v34, 16, 1
	v_bfe_u32 v44, v41, 16, 1
	v_bfe_u32 v45, v40, 16, 1
	v_add3_u32 v40, v40, v45, s68
	v_add3_u32 v41, v41, v44, s68
	v_add3_u32 v34, v34, v37, s68
	v_add3_u32 v35, v35, v36, s68
	v_bfe_u32 v36, v38, 16, 1
	v_bfe_u32 v37, v39, 16, 1
	v_bfe_u32 v44, v42, 16, 1
	v_bfe_u32 v45, v43, 16, 1
	v_add3_u32 v43, v43, v45, s68
	v_add3_u32 v42, v42, v44, s68
	v_add3_u32 v37, v39, v37, s68
	v_add3_u32 v36, v38, v36, s68
	v_lshrrev_b32_e32 v38, 16, v36
	v_lshrrev_b32_e32 v39, 16, v37
	v_lshrrev_b32_e32 v36, 16, v42
	v_lshrrev_b32_e32 v37, 16, v43
	v_and_or_b32 v37, v35, s82, v37
	v_and_or_b32 v36, v34, s82, v36
	v_and_or_b32 v35, v41, s82, v39
	v_and_or_b32 v34, v40, s82, v38
	ds_read_b128 v[42:45], v191 offset:32768
	global_store_dwordx4 v[32:33], v[34:37], off
	v_and_b32_e32 v46, 0xffffffc0, v191
	ds_read_b128 v[50:53], v46
	ds_read_b128 v[54:57], v46 offset:16
	ds_read_b128 v[58:61], v46 offset:32
	s_waitcnt lgkmcnt(0)
	global_store_dwordx4 v[32:33], v[50:53], off offset:-48
	global_store_dwordx4 v[32:33], v[54:57], off offset:-32
	global_store_dwordx4 v[32:33], v[58:61], off offset:-16
	v_add_u32_e32 v32, 0x20c00, v192
	ds_read_b32 v40, v32
	s_waitcnt lgkmcnt(1)
	v_and_b32_e32 v35, 0xffff0000, v43
	v_and_b32_e32 v34, 0xffff0000, v42
	v_and_b32_e32 v39, 0xffff0000, v45
	v_and_b32_e32 v38, 0xffff0000, v44
	v_lshlrev_b32_e32 v33, 16, v43
	v_lshlrev_b32_e32 v32, 16, v42
	s_waitcnt lgkmcnt(0)
	v_pk_mul_f32 v[34:35], v[40:41], v[34:35] op_sel_hi:[0,1]
	v_lshlrev_b32_e32 v37, 16, v45
	v_lshlrev_b32_e32 v36, 16, v44
	v_pk_mul_f32 v[38:39], v[40:41], v[38:39] op_sel_hi:[0,1]
	v_pk_mul_f32 v[32:33], v[40:41], v[32:33] op_sel_hi:[0,1]
	v_pk_mul_f32 v[36:37], v[40:41], v[36:37] op_sel_hi:[0,1]
	v_bfe_u32 v41, v39, 16, 1
	v_bfe_u32 v42, v38, 16, 1
	v_bfe_u32 v43, v35, 16, 1
	v_bfe_u32 v44, v34, 16, 1
	v_add3_u32 v44, v34, v44, s68
	v_add3_u32 v43, v35, v43, s68
	v_add3_u32 v34, v38, v42, s68
	v_add3_u32 v35, v39, v41, s68
	v_bfe_u32 v41, v36, 16, 1
	v_bfe_u32 v42, v37, 16, 1
	v_add3_u32 v37, v37, v42, s68
	v_add3_u32 v36, v36, v41, s68
	v_bfe_u32 v38, v32, 16, 1
	v_bfe_u32 v39, v33, 16, 1
	v_lshrrev_b32_e32 v41, 16, v36
	v_lshrrev_b32_e32 v36, 16, v37
	v_add3_u32 v33, v33, v39, s68
	v_add3_u32 v32, v32, v38, s68
	v_and_or_b32 v35, v35, s82, v36
	ds_read_b128 v[36:39], v190 offset:32768
	v_lshrrev_b32_e32 v32, 16, v32
	v_lshrrev_b32_e32 v33, 16, v33
	v_and_or_b32 v34, v34, s82, v41
	v_and_or_b32 v33, v43, s82, v33
	v_and_or_b32 v32, v44, s82, v32
	ds_write_b128 v191, v[32:35] offset:32768
	s_waitcnt lgkmcnt(1)
	v_lshlrev_b32_e32 v33, 16, v37
	v_lshlrev_b32_e32 v32, 16, v36
	v_and_b32_e32 v35, 0xffff0000, v37
	v_and_b32_e32 v34, 0xffff0000, v36
	v_lshlrev_b32_e32 v37, 16, v39
	v_lshlrev_b32_e32 v36, 16, v38
	v_and_b32_e32 v39, 0xffff0000, v39
	v_and_b32_e32 v38, 0xffff0000, v38
	v_pk_mul_f32 v[34:35], v[40:41], v[34:35] op_sel_hi:[0,1]
	v_pk_mul_f32 v[38:39], v[40:41], v[38:39] op_sel_hi:[0,1]
	v_pk_mul_f32 v[32:33], v[40:41], v[32:33] op_sel_hi:[0,1]
	v_pk_mul_f32 v[36:37], v[40:41], v[36:37] op_sel_hi:[0,1]
	v_bfe_u32 v41, v39, 16, 1
	v_bfe_u32 v42, v38, 16, 1
	v_bfe_u32 v43, v35, 16, 1
	v_bfe_u32 v44, v34, 16, 1
	v_add3_u32 v44, v34, v44, s68
	v_add3_u32 v43, v35, v43, s68
	v_add3_u32 v34, v38, v42, s68
	v_add3_u32 v35, v39, v41, s68
	v_bfe_u32 v41, v36, 16, 1
	v_bfe_u32 v42, v37, 16, 1
	v_add3_u32 v37, v37, v42, s68
	v_add3_u32 v36, v36, v41, s68
	v_bfe_u32 v38, v32, 16, 1
	v_bfe_u32 v39, v33, 16, 1
	v_lshrrev_b32_e32 v41, 16, v36
	v_lshrrev_b32_e32 v36, 16, v37
	v_add3_u32 v33, v33, v39, s68
	v_add3_u32 v32, v32, v38, s68
	v_and_or_b32 v35, v35, s82, v36
	ds_read_b128 v[36:39], v161 offset:32768
	v_lshrrev_b32_e32 v32, 16, v32
	v_lshrrev_b32_e32 v33, 16, v33
	v_and_or_b32 v34, v34, s82, v41
	v_and_or_b32 v33, v43, s82, v33
	v_and_or_b32 v32, v44, s82, v32
	ds_write_b128 v190, v[32:35] offset:32768
	s_waitcnt lgkmcnt(1)
	v_lshlrev_b32_e32 v33, 16, v37
	v_lshlrev_b32_e32 v32, 16, v36
	v_and_b32_e32 v35, 0xffff0000, v37
	v_and_b32_e32 v34, 0xffff0000, v36
	v_pk_mul_f32 v[36:37], v[40:41], v[32:33] op_sel_hi:[0,1]
	v_pk_mul_f32 v[32:33], v[40:41], v[34:35] op_sel_hi:[0,1]
	v_lshlrev_b32_e32 v35, 16, v39
	v_lshlrev_b32_e32 v34, 16, v38
	v_and_b32_e32 v39, 0xffff0000, v39
	v_and_b32_e32 v38, 0xffff0000, v38
	v_pk_mul_f32 v[42:43], v[40:41], v[34:35] op_sel_hi:[0,1]
	v_pk_mul_f32 v[34:35], v[40:41], v[38:39] op_sel_hi:[0,1]
	v_bfe_u32 v38, v35, 16, 1
	v_bfe_u32 v44, v32, 16, 1
	v_bfe_u32 v39, v34, 16, 1
	v_bfe_u32 v41, v33, 16, 1
	v_add3_u32 v32, v32, v44, s68
	v_add3_u32 v35, v35, v38, s68
	v_bfe_u32 v38, v36, 16, 1
	v_bfe_u32 v44, v43, 16, 1
	v_add3_u32 v33, v33, v41, s68
	v_add3_u32 v34, v34, v39, s68
	v_bfe_u32 v39, v37, 16, 1
	v_bfe_u32 v41, v42, 16, 1
	v_add3_u32 v44, v43, v44, s68
	v_add3_u32 v36, v36, v38, s68
	v_add3_u32 v43, v42, v41, s68
	v_add3_u32 v37, v37, v39, s68
	v_lshrrev_b32_e32 v41, 16, v36
	v_lshrrev_b32_e32 v36, 16, v44
	v_lshrrev_b32_e32 v42, 16, v37
	v_and_or_b32 v35, v35, s82, v36
	ds_read_b128 v[36:39], v117 offset:32768
	v_lshrrev_b32_e32 v43, 16, v43
	v_and_or_b32 v34, v34, s82, v43
	v_and_or_b32 v33, v33, s82, v42
	v_and_or_b32 v32, v32, s82, v41
	ds_write_b128 v161, v[32:35] offset:32768
	s_waitcnt lgkmcnt(1)
	v_lshlrev_b32_e32 v33, 16, v37
	v_lshlrev_b32_e32 v32, 16, v36
	v_and_b32_e32 v35, 0xffff0000, v37
	v_and_b32_e32 v34, 0xffff0000, v36
	v_lshlrev_b32_e32 v37, 16, v39
	v_lshlrev_b32_e32 v36, 16, v38
	v_and_b32_e32 v39, 0xffff0000, v39
	v_and_b32_e32 v38, 0xffff0000, v38
	v_pk_mul_f32 v[34:35], v[40:41], v[34:35] op_sel_hi:[0,1]
	v_pk_mul_f32 v[38:39], v[40:41], v[38:39] op_sel_hi:[0,1]
	v_pk_mul_f32 v[32:33], v[40:41], v[32:33] op_sel_hi:[0,1]
	v_pk_mul_f32 v[36:37], v[40:41], v[36:37] op_sel_hi:[0,1]
	v_bfe_u32 v40, v39, 16, 1
	v_bfe_u32 v41, v38, 16, 1
	v_bfe_u32 v42, v35, 16, 1
	v_bfe_u32 v43, v34, 16, 1
	v_add3_u32 v43, v34, v43, s68
	v_add3_u32 v42, v35, v42, s68
	v_add3_u32 v34, v38, v41, s68
	v_add3_u32 v35, v39, v40, s68
	v_bfe_u32 v38, v32, 16, 1
	v_bfe_u32 v39, v33, 16, 1
	v_bfe_u32 v40, v36, 16, 1
	v_bfe_u32 v41, v37, 16, 1
	v_add3_u32 v37, v37, v41, s68
	v_add3_u32 v36, v36, v40, s68
	v_add3_u32 v33, v33, v39, s68
	v_add3_u32 v32, v32, v38, s68
	v_lshrrev_b32_e32 v32, 16, v32
	v_lshrrev_b32_e32 v33, 16, v33
	v_lshrrev_b32_e32 v36, 16, v36
	v_lshrrev_b32_e32 v37, 16, v37
	v_and_or_b32 v35, v35, s82, v37
	v_and_or_b32 v34, v34, s82, v36
	v_and_or_b32 v33, v42, s82, v33
	v_and_or_b32 v32, v43, s82, v32
	ds_write_b128 v117, v[32:35] offset:32768
	s_and_saveexec_b64 s[0:1], s[8:9]
	s_cbranch_execz .LBB0_775
	v_lshl_add_u32 v32, v132, 2, 0
	v_add_u32_e32 v32, 0x20e00, v32
	ds_read_b32 v33, v32
	s_waitcnt lgkmcnt(0)
	v_mul_f32_e32 v33, v109, v33
	ds_write_b32 v32, v33
